# mix pass P epilogue: pool_scale chunks loaded once per workgroup, 8-step load/wait/store ladder removed
# speedup vs baseline: 1.0035x; 1.0035x over previous
; __device__ __forceinline__ unsigned cvt_pk(float lo, float hi) { unsigned r; asm volatile("v_cvt_pk_bf16_f32 %0, %1, %2" : "=v"(r) : "v"(lo), "v"(hi)); return r; }
; __device__ __forceinline__ float bflo(unsigned w) { return __uint_as_float(w << 16); }
; __device__ __forceinline__ float bfhi(unsigned w) { return __uint_as_float(w & 0xffff0000u); }
; __device__ void phase_mix(const Params& p, unsigned char* smem) {
;     ...
;     const int g = blockIdx.x & 3;
;     stage_tile(Bs, (const bf16_t*)(p.ws + OFF_WPT) + g * 16384, 128);
;     const int tstep = gridDim.x >> 2, tlim = (REP_PH == 2 ? 1024 : 512);
;     ...
;     {
;         const int left = 1 << g, right = (1 << g) - 1;
;         u32x4 hreg[5];
;     ...
;         HLOAD(blockIdx.x >> 2);
;         for (int tile_ = blockIdx.x >> 2; tile_ < tlim; tile_ += tstep) {
;             TILE_DECODE(tile_);
; #pragma unroll
;             for (int i = 0; i < 5; ++i) { const int idx = tid + 512 * i; if (idx < 2304) *(u32x4*)(halo + (idx >> 4) * 256 + (idx & 15) * 16) = hreg[i]; }
;             const size_t r = (size_t)r0 + wid * 16 + li;
;             u32x2 zreg[8];
; #pragma unroll
;             for (int nb = 0; nb < 8; ++nb) zreg[nb] = *(const u32x2*)(P0 + r * LDP + 512 + g * 128 + nb * 16 + kq * 4);
;             __syncthreads();
;             { const int c2 = tid & 63, tq = tid >> 6;
;               float s0 = 0.f, s1 = 0.f; const int tl0 = tq * 16;
;               for (int j = tl0 - left; j <= tl0 + right; ++j) { const unsigned w = *(const unsigned*)(halo + (j + 8) * 256 + c2 * 4); s0 += bflo(w); s1 += bfhi(w); }
;               for (int tl = tl0; tl < tl0 + 16; ++tl) { const int t = ts0 + tl; const int lo = max(t - left, 0), hi = min(t + right + 1, T);
;                   const float inv = __builtin_amdgcn_rcpf((float)(hi - lo)); const unsigned xw = *(const unsigned*)(halo + (tl + 8) * 256 + c2 * 4);
;                   *(unsigned*)(As + swz(tl, c2 >> 2) + (c2 & 3) * 4) = cvt_pk(s0 * inv - bflo(xw), s1 * inv - bfhi(xw));
;                   const unsigned wn = *(const unsigned*)(halo + (tl + 1 + right + 8) * 256 + c2 * 4), wo = *(const unsigned*)(halo + (tl - left + 8) * 256 + c2 * 4);
;                   s0 += bflo(wn) - bflo(wo); s1 += bfhi(wn) - bfhi(wo); } }
;             __syncthreads();
;             HLOAD((tile_ + tstep < tlim) ? tile_ + tstep : tile_);
;             bf16x8 af[4]; ldfrag(af, As, wid, lane);
.LBB0_142:
	s_or_b64 exec, exec, s[0:1]
	s_lshr_b32 s3, s82, 2
	s_lshr_b32 s24, s2, 2
	v_and_b32_e32 v96, 15, v94
	v_bfe_u32 v21, v94, 4, 2
	s_cmpk_lt_u32 s2, 0x800
	v_ashrrev_i32_e32 v95, 6, v94
	s_cselect_b64 s[18:19], -1, 0
	v_xor_b32_e32 v26, v21, v96
	s_and_b64 vcc, exec, s[18:19]
	v_lshlrev_b32_e32 v97, 4, v95
	v_lshlrev_b32_e32 v98, 8, v96
	v_lshlrev_b32_e32 v104, 4, v26
	v_bitop3_b32 v101, v21, v96, 4 bitop3:0x36
	v_bitop3_b32 v100, v21, v96, 8 bitop3:0x36
	v_bitop3_b32 v99, v21, v96, 12 bitop3:0x36
	v_lshlrev_b32_e32 v80, 3, v21
	s_cbranch_vccz .LBB0_169
	v_and_b32_e32 v27, 0xf0, v20
	v_and_b32_e32 v36, 0xffffff00, v20
	v_lshlrev_b32_e32 v20, 4, v22
	v_and_b32_e32 v22, 0xffffff00, v20
	v_lshlrev_b32_e32 v20, 4, v23
	v_and_b32_e32 v26, 63, v94
	v_and_b32_e32 v23, 0xffffff00, v20
	v_lshlrev_b32_e32 v20, 4, v24
	v_lshlrev_b32_e32 v26, 2, v26
	v_and_b32_e32 v24, 0xffffff00, v20
	v_lshlrev_b32_e32 v20, 4, v25
	s_lshl_b32 s29, 1, s14
	v_lshlrev_b32_e32 v30, 12, v95
	v_and_b32_e32 v25, 0xffffff00, v20
	v_and_b32_e32 v20, 0xf0, v26
	s_add_i32 s30, 0, 0x10000
	v_add3_u32 v38, 0, v20, v30
	v_or_b32_e32 v83, 1, v97
	v_or_b32_e32 v20, s29, v97
	v_mov_b32_e32 v46, 0xf0
	v_lshl_add_u32 v39, v20, 8, s30
	v_lshlrev_b32_e32 v20, 8, v83
	v_bitop3_b32 v47, v26, 16, v46 bitop3:0x6c
	v_add_u32_e32 v53, s30, v20
	v_add3_u32 v54, 0, v47, v20
	v_add_u32_e32 v20, s29, v83
	v_or_b32_e32 v85, 2, v97
	v_lshl_add_u32 v55, v20, 8, s30
	v_subrev_u32_e32 v20, s29, v83
	v_lshl_add_u32 v56, v20, 8, s30
	v_lshlrev_b32_e32 v20, 8, v85
	v_bitop3_b32 v47, v26, 32, v46 bitop3:0x6c
	v_add_u32_e32 v57, s30, v20
	v_add3_u32 v58, 0, v47, v20
	v_add_u32_e32 v20, s29, v85
	v_or_b32_e32 v86, 3, v97
	v_lshl_add_u32 v59, v20, 8, s30
	v_subrev_u32_e32 v20, s29, v85
	v_lshl_add_u32 v60, v20, 8, s30
	v_lshlrev_b32_e32 v20, 8, v86
	v_bitop3_b32 v47, v26, 48, v46 bitop3:0x6c
	v_add_u32_e32 v61, s30, v20
	v_add3_u32 v62, 0, v47, v20
	v_add_u32_e32 v20, s29, v86
	v_or_b32_e32 v87, 4, v97
	v_lshl_add_u32 v63, v20, 8, s30
	v_subrev_u32_e32 v20, s29, v86
	v_lshl_add_u32 v64, v20, 8, s30
	v_lshlrev_b32_e32 v20, 8, v87
	v_bitop3_b32 v47, v26, 64, v46 bitop3:0x6c
	v_add_u32_e32 v65, s30, v20
	v_add3_u32 v66, 0, v47, v20
	v_add_u32_e32 v20, s29, v87
	v_or_b32_e32 v88, 5, v97
	v_lshl_add_u32 v67, v20, 8, s30
	v_subrev_u32_e32 v20, s29, v87
	s_movk_i32 s31, 0x50
	v_lshl_add_u32 v68, v20, 8, s30
	v_lshlrev_b32_e32 v20, 8, v88
	v_bitop3_b32 v47, v26, s31, v46 bitop3:0x6c
	v_add_u32_e32 v69, s30, v20
	v_add3_u32 v135, 0, v47, v20
	v_add_u32_e32 v20, s29, v88
	v_or_b32_e32 v89, 6, v97
	v_lshl_add_u32 v136, v20, 8, s30
	v_subrev_u32_e32 v20, s29, v88
	s_movk_i32 s31, 0x60
	v_lshl_add_u32 v137, v20, 8, s30
	v_lshlrev_b32_e32 v20, 8, v89
	v_bitop3_b32 v47, v26, s31, v46 bitop3:0x6c
	v_add_u32_e32 v138, s30, v20
	v_add3_u32 v139, 0, v47, v20
	v_add_u32_e32 v20, s29, v89
	v_or_b32_e32 v90, 7, v97
	v_lshl_add_u32 v140, v20, 8, s30
	v_subrev_u32_e32 v20, s29, v89
	s_movk_i32 s31, 0x70
	v_lshl_add_u32 v141, v20, 8, s30
	v_lshlrev_b32_e32 v20, 8, v90
	v_bitop3_b32 v47, v26, s31, v46 bitop3:0x6c
	v_add_u32_e32 v142, s30, v20
	v_add3_u32 v143, 0, v47, v20
	v_add_u32_e32 v20, s29, v90
	v_or_b32_e32 v91, 8, v97
	v_lshl_add_u32 v144, v20, 8, s30
	v_subrev_u32_e32 v20, s29, v90
	s_movk_i32 s31, 0x80
	v_lshl_add_u32 v145, v20, 8, s30
	v_lshlrev_b32_e32 v20, 8, v91
	v_bitop3_b32 v47, v26, s31, v46 bitop3:0x6c
	v_add_u32_e32 v146, s30, v20
	v_add3_u32 v147, 0, v47, v20
	v_add_u32_e32 v20, s29, v91
	v_or_b32_e32 v92, 9, v97
	v_lshl_add_u32 v148, v20, 8, s30
	v_subrev_u32_e32 v20, s29, v91
	s_movk_i32 s31, 0x90
	v_lshl_add_u32 v149, v20, 8, s30
	v_lshlrev_b32_e32 v20, 8, v92
	v_bitop3_b32 v47, v26, s31, v46 bitop3:0x6c
	v_add_u32_e32 v150, s30, v20
	v_add3_u32 v151, 0, v47, v20
	v_add_u32_e32 v20, s29, v92
	v_or_b32_e32 v93, 10, v97
	v_lshl_add_u32 v152, v20, 8, s30
	v_subrev_u32_e32 v20, s29, v92
	s_movk_i32 s31, 0xa0
	v_lshl_add_u32 v153, v20, 8, s30
	v_lshlrev_b32_e32 v20, 8, v93
	v_bitop3_b32 v47, v26, s31, v46 bitop3:0x6c
	v_add_u32_e32 v154, s30, v20
	v_add3_u32 v155, 0, v47, v20
	v_add_u32_e32 v20, s29, v93
	v_or_b32_e32 v102, 11, v97
	v_lshl_add_u32 v156, v20, 8, s30
	v_subrev_u32_e32 v20, s29, v93
	s_movk_i32 s31, 0xb0
	v_lshl_add_u32 v157, v20, 8, s30
	v_lshlrev_b32_e32 v20, 8, v102
	v_bitop3_b32 v47, v26, s31, v46 bitop3:0x6c
	v_add_u32_e32 v158, s30, v20
	v_add3_u32 v159, 0, v47, v20
	v_add_u32_e32 v20, s29, v102
	v_or_b32_e32 v103, 12, v97
	v_lshl_add_u32 v160, v20, 8, s30
	v_subrev_u32_e32 v20, s29, v102
	s_movk_i32 s31, 0xc0
	v_lshl_add_u32 v161, v20, 8, s30
	v_lshlrev_b32_e32 v20, 8, v103
	v_bitop3_b32 v47, v26, s31, v46 bitop3:0x6c
	v_add_u32_e32 v162, s30, v20
	v_add3_u32 v163, 0, v47, v20
	v_add_u32_e32 v20, s29, v103
	v_or_b32_e32 v105, 13, v97
	v_lshl_add_u32 v164, v20, 8, s30
	v_subrev_u32_e32 v20, s29, v103
	s_movk_i32 s31, 0xd0
	v_lshl_add_u32 v165, v20, 8, s30
	v_lshlrev_b32_e32 v20, 8, v105
	v_bitop3_b32 v47, v26, s31, v46 bitop3:0x6c
	v_add_u32_e32 v166, s30, v20
	v_add3_u32 v167, 0, v47, v20
	v_add_u32_e32 v20, s29, v105
	v_or_b32_e32 v106, 14, v97
	v_lshl_add_u32 v168, v20, 8, s30
	v_subrev_u32_e32 v20, s29, v105
	s_movk_i32 s31, 0xe0
	v_lshl_add_u32 v169, v20, 8, s30
	v_lshlrev_b32_e32 v20, 8, v106
	v_bitop3_b32 v46, v26, s31, v46 bitop3:0x6c
	s_lshl_b32 s22, s28, 1
	v_readlane_b32 s34, v254, 46
	v_add_u32_e32 v171, s30, v20
	v_add3_u32 v172, 0, v46, v20
	v_add_u32_e32 v20, s29, v106
	s_movk_i32 s0, 0xf0
	v_readlane_b32 s35, v254, 47
	s_add_u32 s22, s34, s22
	v_or_b32_e32 v107, 15, v97
	v_lshl_add_u32 v173, v20, 8, s30
	v_subrev_u32_e32 v20, s29, v106
	v_readlane_b32 s36, v254, 0
; __device__ void phase_mix(const Params& p, unsigned char* smem) {
;     ...
;     const int g = blockIdx.x & 3;
;     stage_tile(Bs, (const bf16_t*)(p.ws + OFF_WPT) + g * 16384, 128);
;     const int tstep = gridDim.x >> 2, tlim = (REP_PH == 2 ? 1024 : 512);
;     ...
;     {
;         const int left = 1 << g, right = (1 << g) - 1;
;     ...
;             for (int nb = 0; nb < 8; ++nb) { const int d = nb * 16 + kq * 4;
;                 const u32x2 za = zreg[nb]; const f32x4 ps = *(const f32x4*)(p.pool_scale + g * 128 + d);
	v_subrev_u32_e32 v28, s29, v97
	s_addc_u32 s23, s35, 0
	v_lshl_add_u32 v174, v20, 8, s30
	v_lshlrev_b32_e32 v20, 8, v107
	v_bitop3_b32 v46, v26, s0, v26 bitop3:0xc
	s_lshl_b32 s0, s28, 2
	v_readlane_b32 s44, v254, 8
	v_add_u32_e32 v27, s30, v27
	v_add_u32_e32 v37, s30, v30
	v_lshl_add_u32 v52, v28, 8, s30
	v_add_u32_e32 v175, s30, v20
	v_readlane_b32 s45, v254, 9
	s_add_u32 s30, s44, s0
	v_add3_u32 v177, 0, v46, v20
	s_addc_u32 s31, s45, 0
	v_lshlrev_b32_e32 v20, 4, v21
	v_mov_b32_e32 v21, 0
	v_lshl_add_u64 v[46:47], s[30:31], 0, v[20:21]
	v_or_b32_e32 v20, v30, v26
	s_lshl_b32 s0, s29, 8
	v_lshlrev_b32_e32 v29, 2, v94
	v_lshlrev_b32_e32 v77, 4, v101
	v_lshlrev_b32_e32 v78, 4, v100
	v_lshlrev_b32_e32 v79, 4, v99
	v_subrev_u32_e32 v20, s0, v20
	v_add3_u32 v76, s29, -1, v97
	v_and_b32_e32 v29, 12, v29
	v_or_b32_e32 v31, v98, v30
	v_add_u32_e32 v32, 0, v104
	v_add_u32_e32 v33, 0, v77
	v_add_u32_e32 v34, 0, v78
	v_add_u32_e32 v35, 0, v79
	v_mov_b32_e32 v81, v21
	v_add_u32_e32 v20, 0, v20
	s_mov_b32 s1, 0
	v_ashrrev_i32_e32 v45, 31, v97
	v_or_b32_e32 v44, v97, v96
	v_cmp_le_i32_e64 s[14:15], v28, v76
	v_add_u32_e32 v82, 0, v98
	v_lshl_add_u64 v[48:49], s[20:21], 0, v[80:81]
	v_lshl_add_u64 v[50:51], s[22:23], 0, v[80:81]
	v_add_u32_e32 v81, -1, v28
	v_add_u32_e32 v108, 0x10800, v20
	v_add_u32_e32 v109, v27, v36
	v_add_u32_e32 v110, v27, v22
	v_add_u32_e32 v111, v27, v23
	v_add_u32_e32 v112, v27, v24
	v_add_u32_e32 v113, v27, v25
	s_movk_i32 s30, 0x1800
	s_movk_i32 s31, 0x1000
	s_movk_i32 s33, 0xf80
	v_add_u32_e32 v114, v37, v26
	v_add_u32_e32 v115, v38, v29
	v_add_u32_e32 v116, v39, v26
	v_add_u32_e32 v117, v52, v26
	v_add_u32_e32 v118, v53, v26
	v_add_u32_e32 v119, v54, v29
	v_add_u32_e32 v120, v55, v26
	v_add_u32_e32 v121, v56, v26
	v_add_u32_e32 v122, v57, v26
	v_add_u32_e32 v123, v58, v29
	v_add_u32_e32 v124, v59, v26
	v_add_u32_e32 v125, v60, v26
	v_add_u32_e32 v126, v61, v26
	v_add_u32_e32 v127, v62, v29
	v_add_u32_e32 v128, v63, v26
	v_add_u32_e32 v129, v64, v26
	v_add_u32_e32 v130, v65, v26
	v_add_u32_e32 v131, v66, v29
	v_add_u32_e32 v132, v67, v26
	v_add_u32_e32 v133, v68, v26
	v_add_u32_e32 v134, v69, v26
	v_add_u32_e32 v135, v135, v29
	v_add_u32_e32 v136, v136, v26
	v_add_u32_e32 v137, v137, v26
	v_add_u32_e32 v138, v138, v26
	v_add_u32_e32 v139, v139, v29
	v_add_u32_e32 v140, v140, v26
	v_add_u32_e32 v141, v141, v26
	v_add_u32_e32 v142, v142, v26
	v_add_u32_e32 v143, v143, v29
	v_add_u32_e32 v144, v144, v26
	v_add_u32_e32 v145, v145, v26
	v_add_u32_e32 v146, v146, v26
	v_add_u32_e32 v147, v147, v29
	v_add_u32_e32 v148, v148, v26
	v_add_u32_e32 v149, v149, v26
	v_add_u32_e32 v150, v150, v26
	v_add_u32_e32 v151, v151, v29
	v_add_u32_e32 v152, v152, v26
	v_add_u32_e32 v153, v153, v26
	v_add_u32_e32 v154, v154, v26
	v_add_u32_e32 v155, v155, v29
	v_add_u32_e32 v156, v156, v26
	v_add_u32_e32 v157, v157, v26
	v_add_u32_e32 v158, v158, v26
	v_add_u32_e32 v159, v159, v29
	v_add_u32_e32 v160, v160, v26
	v_add_u32_e32 v161, v161, v26
	v_add_u32_e32 v162, v162, v26
	v_add_u32_e32 v163, v163, v29
	v_add_u32_e32 v164, v164, v26
	v_add_u32_e32 v165, v165, v26
	v_add_u32_e32 v166, v166, v26
	v_add_u32_e32 v167, v167, v29
	v_add_u32_e32 v168, v168, v26
	v_add_u32_e32 v169, v169, v26
	v_add_u32_e32 v171, v171, v26
	v_add_u32_e32 v172, v172, v29
	v_add_u32_e32 v173, v173, v26
	v_add_u32_e32 v174, v174, v26
	v_add_u32_e32 v175, v175, v26
	v_add_u32_e32 v177, v177, v29
	v_add_u32_e32 v178, v32, v31
	v_add_u32_e32 v179, v33, v31
	v_add_u32_e32 v180, v34, v31
	v_add_u32_e32 v181, v35, v31
	s_mov_b32 s34, s24
	v_readlane_b32 s37, v254, 1
	v_readlane_b32 s38, v254, 2
	v_readlane_b32 s39, v254, 3
	v_readlane_b32 s40, v254, 4
	v_readlane_b32 s41, v254, 5
	v_readlane_b32 s42, v254, 6
	v_readlane_b32 s43, v254, 7
	v_readlane_b32 s46, v254, 10
	v_readlane_b32 s47, v254, 11
	v_readlane_b32 s48, v254, 12
	v_readlane_b32 s49, v254, 13
	v_readlane_b32 s50, v254, 14
	v_readlane_b32 s51, v254, 15
	global_load_dwordx4 v[216:219], v[46:47], off
	global_load_dwordx4 v[220:223], v[46:47], off offset:64
	global_load_dwordx4 v[224:227], v[46:47], off offset:128
	global_load_dwordx4 v[228:231], v[46:47], off offset:192
	global_load_dwordx4 v[232:235], v[46:47], off offset:256
	global_load_dwordx4 v[236:239], v[46:47], off offset:320
	global_load_dwordx4 v[240:243], v[46:47], off offset:384
	global_load_dwordx4 v[244:247], v[46:47], off offset:448
	s_branch .LBB0_145
; template <int NB> __device__ __forceinline__ void mm16(f32x4 (&acc)[NB], const unsigned char* Xs, const bf16x8 (&yf)[4], int lane) {
;     const int i = lane & 15, kq = lane >> 4;
; #pragma unroll
;     for (int ks = 0; ks < 4; ++ks)
; #pragma unroll
;         for (int nb = 0; nb < NB; ++nb) {
;             const bf16x8 x = *(const bf16x8*)(Xs + swz(nb * 16 + i, ks * 4 + kq));
;             acc[nb] = __builtin_amdgcn_mfma_f32_16x16x32_bf16(x, yf[ks], acc[nb], 0, 0, 0);
;             if ((nb & 3) == 3) __builtin_amdgcn_sched_barrier(0);
;         }
; }
; __device__ void phase_mix(const Params& p, unsigned char* smem) {
;     ...
;             bf16x8 af[4]; ldfrag(af, As, wid, lane);
;             f32x4 acc[8];
; #pragma unroll
;             for (int nb = 0; nb < 8; ++nb) acc[nb] = (f32x4){0.f, 0.f, 0.f, 0.f};
;             mm16<8>(acc, Bs, af, lane);
.LBB0_144:
	s_or_b64 exec, exec, s[22:23]
	v_add_u32_e32 v206, v82, v104
	ds_read_b128 v[20:23], v206 offset:32768
	ds_read_b128 v[24:27], v206 offset:36864
	ds_read_b128 v[28:31], v178
	ds_read_b128 v[32:35], v179
	ds_read_b128 v[36:39], v206 offset:40960
	ds_read_b128 v[182:185], v206 offset:45056
	ds_read_b128 v[186:189], v180
	ds_read_b128 v[190:193], v181
	s_waitcnt lgkmcnt(5)
	v_mfma_f32_16x16x32_bf16 v[20:23], v[20:23], v[28:31], 0
	v_mfma_f32_16x16x32_bf16 v[24:27], v[24:27], v[28:31], 0
	s_waitcnt lgkmcnt(3)
	v_mfma_f32_16x16x32_bf16 v[36:39], v[36:39], v[28:31], 0
	s_waitcnt lgkmcnt(2)
	v_mfma_f32_16x16x32_bf16 v[182:185], v[182:185], v[28:31], 0
	ds_read_b128 v[194:197], v206 offset:49152
	ds_read_b128 v[198:201], v206 offset:53248
	ds_read_b128 v[202:205], v206 offset:57344
	ds_read_b128 v[206:209], v206 offset:61440
	s_waitcnt lgkmcnt(3)
	v_mfma_f32_16x16x32_bf16 v[194:197], v[194:197], v[28:31], 0
	s_waitcnt lgkmcnt(2)
	v_mfma_f32_16x16x32_bf16 v[198:201], v[198:201], v[28:31], 0
	s_waitcnt lgkmcnt(1)
	v_mfma_f32_16x16x32_bf16 v[202:205], v[202:205], v[28:31], 0
	s_waitcnt lgkmcnt(0)
	v_mfma_f32_16x16x32_bf16 v[28:31], v[206:209], v[28:31], 0
	v_add_u32_e32 v214, v82, v77
	ds_read_b128 v[206:209], v214 offset:32768
	ds_read_b128 v[210:213], v214 offset:36864
	s_waitcnt lgkmcnt(1)
	v_mfma_f32_16x16x32_bf16 v[20:23], v[206:209], v[32:35], v[20:23]
	ds_read_b128 v[206:209], v214 offset:40960
	s_waitcnt lgkmcnt(1)
	v_mfma_f32_16x16x32_bf16 v[24:27], v[210:213], v[32:35], v[24:27]
	ds_read_b128 v[210:213], v214 offset:45056
	s_waitcnt lgkmcnt(1)
	v_mfma_f32_16x16x32_bf16 v[36:39], v[206:209], v[32:35], v[36:39]
	s_waitcnt lgkmcnt(0)
	v_mfma_f32_16x16x32_bf16 v[182:185], v[210:213], v[32:35], v[182:185]
	ds_read_b128 v[206:209], v214 offset:49152
	ds_read_b128 v[210:213], v214 offset:53248
	s_waitcnt lgkmcnt(1)
	v_mfma_f32_16x16x32_bf16 v[194:197], v[206:209], v[32:35], v[194:197]
	ds_read_b128 v[206:209], v214 offset:57344
	s_waitcnt lgkmcnt(1)
	v_mfma_f32_16x16x32_bf16 v[198:201], v[210:213], v[32:35], v[198:201]
	ds_read_b128 v[210:213], v214 offset:61440
	s_waitcnt lgkmcnt(1)
	v_mfma_f32_16x16x32_bf16 v[202:205], v[206:209], v[32:35], v[202:205]
	s_waitcnt lgkmcnt(0)
	v_mfma_f32_16x16x32_bf16 v[28:31], v[210:213], v[32:35], v[28:31]
	v_add_u32_e32 v210, v82, v78
	ds_read_b128 v[32:35], v210 offset:32768
	ds_read_b128 v[206:209], v210 offset:36864
	s_waitcnt lgkmcnt(1)
	v_mfma_f32_16x16x32_bf16 v[20:23], v[32:35], v[186:189], v[20:23]
	ds_read_b128 v[32:35], v210 offset:40960
	s_waitcnt lgkmcnt(1)
	v_mfma_f32_16x16x32_bf16 v[24:27], v[206:209], v[186:189], v[24:27]
	ds_read_b128 v[206:209], v210 offset:45056
	s_waitcnt lgkmcnt(1)
	v_mfma_f32_16x16x32_bf16 v[32:35], v[32:35], v[186:189], v[36:39]
	s_waitcnt lgkmcnt(0)
	v_mfma_f32_16x16x32_bf16 v[36:39], v[206:209], v[186:189], v[182:185]
	s_nop 2
	ds_read_b128 v[182:185], v210 offset:49152
	ds_read_b128 v[206:209], v210 offset:53248
	s_waitcnt lgkmcnt(1)
	v_mfma_f32_16x16x32_bf16 v[182:185], v[182:185], v[186:189], v[194:197]
	s_nop 2
	ds_read_b128 v[194:197], v210 offset:57344
	s_waitcnt lgkmcnt(1)
	v_mfma_f32_16x16x32_bf16 v[198:201], v[206:209], v[186:189], v[198:201]
	ds_read_b128 v[206:209], v210 offset:61440
	s_waitcnt lgkmcnt(1)
	v_mfma_f32_16x16x32_bf16 v[194:197], v[194:197], v[186:189], v[202:205]
	s_waitcnt lgkmcnt(0)
	v_mfma_f32_16x16x32_bf16 v[186:189], v[206:209], v[186:189], v[28:31]
	v_add_u32_e32 v214, v82, v79
	s_nop 1
	ds_read_b128 v[28:31], v214 offset:32768
	ds_read_b128 v[202:205], v214 offset:36864
	s_waitcnt lgkmcnt(1)
	v_mfma_f32_16x16x32_bf16 v[206:209], v[28:31], v[190:193], v[20:23]
	s_nop 2
	ds_read_b128 v[20:23], v214 offset:40960
	s_waitcnt lgkmcnt(1)
	v_mfma_f32_16x16x32_bf16 v[202:205], v[202:205], v[190:193], v[24:27]
	s_nop 2
	ds_read_b128 v[24:27], v214 offset:45056
	s_waitcnt lgkmcnt(1)
	v_mfma_f32_16x16x32_bf16 v[210:213], v[20:23], v[190:193], v[32:35]
	s_waitcnt lgkmcnt(0)
	v_mfma_f32_16x16x32_bf16 v[36:39], v[24:27], v[190:193], v[36:39]
	ds_read_b128 v[20:23], v214 offset:49152
	ds_read_b128 v[24:27], v214 offset:53248
	s_waitcnt lgkmcnt(1)
	v_mfma_f32_16x16x32_bf16 v[32:35], v[20:23], v[190:193], v[182:185]
	ds_read_b128 v[20:23], v214 offset:57344
	s_nop 1
	ds_read_b128 v[182:185], v214 offset:61440
	s_waitcnt lgkmcnt(2)
	v_mfma_f32_16x16x32_bf16 v[28:31], v[24:27], v[190:193], v[198:201]
	s_waitcnt lgkmcnt(1)
	v_mfma_f32_16x16x32_bf16 v[24:27], v[20:23], v[190:193], v[194:197]
	s_waitcnt lgkmcnt(0)
; __device__ __forceinline__ unsigned cvt_pk(float lo, float hi) { unsigned r; asm volatile("v_cvt_pk_bf16_f32 %0, %1, %2" : "=v"(r) : "v"(lo), "v"(hi)); return r; }
; __device__ __forceinline__ float bflo(unsigned w) { return __uint_as_float(w << 16); }
; __device__ __forceinline__ float bfhi(unsigned w) { return __uint_as_float(w & 0xffff0000u); }
; __device__ __forceinline__ float silu(float x) { return x * sigm(x); }
; __device__ void phase_mix(const Params& p, unsigned char* smem) {
;     ...
; #pragma unroll
;             for (int nb = 0; nb < 8; ++nb) { const int d = nb * 16 + kq * 4;
;                 const u32x2 za = zreg[nb]; const f32x4 ps = *(const f32x4*)(p.pool_scale + g * 128 + d);
;                 u32x2 o; o.x = cvt_pk(acc[nb][0] * ps[0] * silu(bflo(za.x)), acc[nb][1] * ps[1] * silu(bfhi(za.x)));
;                 o.y = cvt_pk(acc[nb][2] * ps[2] * silu(bflo(za.y)), acc[nb][3] * ps[3] * silu(bfhi(za.y)));
;                 *(u32x2*)(CAT0 + r * 1024 + g * 128 + d) = o; }
	v_mfma_f32_16x16x32_bf16 v[20:23], v[182:185], v[190:193], v[186:189]
	v_mov_b64_e32 v[182:183], v[216:217]
	v_mov_b64_e32 v[184:185], v[218:219]
	s_nop 0
	v_lshlrev_b32_e32 v186, 16, v66
	v_lshlrev_b32_e32 v190, 16, v67
	v_mul_f32_e32 v187, 0xbfb8aa3b, v186
	v_mul_f32_e32 v188, 0xbfb8aa3b, v190
	v_exp_f32_e32 v187, v187
	v_exp_f32_e32 v188, v188
	v_mov_b32_e32 v189, v206
	v_mov_b32_e32 v193, v208
	v_add_f32_e32 v187, 1.0, v187
	v_add_f32_e32 v191, 1.0, v188
	v_rcp_f32_e32 v188, v187
	v_rcp_f32_e32 v192, v191
	v_lshlrev_b64 v[68:69], 11, v[68:69]
	v_lshl_add_u64 v[68:69], v[50:51], 0, v[68:69]
	s_and_b64 vcc, exec, s[20:21]
	s_mov_b32 s34, s0
	v_mov_b32_e32 v187, v182
	v_and_b32_e32 v182, 0xffff0000, v66
	v_mov_b32_e32 v191, v184
	v_and_b32_e32 v184, 0xffff0000, v67
	v_mul_f32_e32 v66, 0xbfb8aa3b, v182
	v_mul_f32_e32 v67, 0xbfb8aa3b, v184
	v_exp_f32_e32 v194, v66
	v_exp_f32_e32 v195, v67
	v_pk_mul_f32 v[66:67], v[188:189], v[186:187]
	v_pk_mul_f32 v[186:187], v[192:193], v[190:191]
	v_add_f32_e32 v188, 1.0, v194
	v_add_f32_e32 v189, 1.0, v195
	v_rcp_f32_e32 v206, v188
	v_rcp_f32_e32 v208, v189
	v_mul_f32_e32 v188, v66, v67
	v_mul_f32_e32 v186, v186, v187
	v_pk_mul_f32 v[66:67], v[206:207], v[182:183]
	v_pk_mul_f32 v[182:183], v[208:209], v[184:185]
	v_mul_f32_e32 v66, v66, v67
	v_mul_f32_e32 v67, v182, v183
	v_cvt_pk_bf16_f32 v66, v188, v66
	v_cvt_pk_bf16_f32 v67, v186, v67
	global_store_dwordx2 v[68:69], v[66:67], off
	v_mov_b64_e32 v[182:183], v[220:221]
	v_mov_b64_e32 v[184:185], v[222:223]
	v_lshlrev_b32_e32 v66, 16, v64
	v_lshlrev_b32_e32 v186, 16, v65
	v_mul_f32_e32 v67, 0xbfb8aa3b, v66
	v_mul_f32_e32 v187, 0xbfb8aa3b, v186
	v_exp_f32_e32 v67, v67
	v_exp_f32_e32 v187, v187
	v_mov_b32_e32 v189, v202
	v_mov_b32_e32 v191, v204
	v_add_f32_e32 v67, 1.0, v67
	v_add_f32_e32 v187, 1.0, v187
	v_rcp_f32_e32 v188, v67
	v_rcp_f32_e32 v190, v187
	v_mov_b32_e32 v67, v182
	v_and_b32_e32 v182, 0xffff0000, v64
	v_mov_b32_e32 v187, v184
	v_and_b32_e32 v184, 0xffff0000, v65
	v_mul_f32_e32 v64, 0xbfb8aa3b, v182
	v_mul_f32_e32 v65, 0xbfb8aa3b, v184
	v_exp_f32_e32 v192, v64
	v_exp_f32_e32 v193, v65
	v_pk_mul_f32 v[64:65], v[188:189], v[66:67]
	v_pk_mul_f32 v[66:67], v[190:191], v[186:187]
	v_add_f32_e32 v186, 1.0, v192
	v_add_f32_e32 v187, 1.0, v193
	v_rcp_f32_e32 v202, v186
	v_rcp_f32_e32 v204, v187
	v_mul_f32_e32 v186, v64, v65
	v_mul_f32_e32 v187, v66, v67
	v_pk_mul_f32 v[64:65], v[202:203], v[182:183]
	v_pk_mul_f32 v[66:67], v[204:205], v[184:185]
	v_mul_f32_e32 v64, v64, v65
	v_mul_f32_e32 v65, v66, v67
	v_cvt_pk_bf16_f32 v64, v186, v64
	v_cvt_pk_bf16_f32 v65, v187, v65
	global_store_dwordx2 v[68:69], v[64:65], off offset:32
	v_mov_b64_e32 v[64:65], v[224:225]
	v_mov_b64_e32 v[66:67], v[226:227]
	v_lshlrev_b32_e32 v182, 16, v62
	v_lshlrev_b32_e32 v184, 16, v63
	v_mul_f32_e32 v183, 0xbfb8aa3b, v182
	v_mul_f32_e32 v185, 0xbfb8aa3b, v184
	v_exp_f32_e32 v183, v183
	v_exp_f32_e32 v185, v185
	v_mov_b32_e32 v187, v210
	v_mov_b32_e32 v189, v212
	v_add_f32_e32 v183, 1.0, v183
	v_add_f32_e32 v185, 1.0, v185
	v_rcp_f32_e32 v186, v183
	v_rcp_f32_e32 v188, v185
	v_mov_b32_e32 v183, v64
	v_and_b32_e32 v64, 0xffff0000, v62
	v_mov_b32_e32 v185, v66
	v_and_b32_e32 v66, 0xffff0000, v63
	v_mul_f32_e32 v62, 0xbfb8aa3b, v64
	v_mul_f32_e32 v63, 0xbfb8aa3b, v66
	v_exp_f32_e32 v190, v62
	v_exp_f32_e32 v191, v63
	v_pk_mul_f32 v[62:63], v[186:187], v[182:183]
	v_pk_mul_f32 v[182:183], v[188:189], v[184:185]
	v_add_f32_e32 v184, 1.0, v190
	v_add_f32_e32 v185, 1.0, v191
	v_rcp_f32_e32 v210, v184
	v_rcp_f32_e32 v212, v185
	v_mul_f32_e32 v184, v62, v63
	v_mul_f32_e32 v182, v182, v183
	v_pk_mul_f32 v[62:63], v[210:211], v[64:65]
	v_pk_mul_f32 v[64:65], v[212:213], v[66:67]
	v_mul_f32_e32 v62, v62, v63
	v_mul_f32_e32 v63, v64, v65
	v_cvt_pk_bf16_f32 v62, v184, v62
	v_cvt_pk_bf16_f32 v63, v182, v63
	global_store_dwordx2 v[68:69], v[62:63], off offset:64
	v_mov_b64_e32 v[62:63], v[228:229]
	v_mov_b64_e32 v[64:65], v[230:231]
	v_lshlrev_b32_e32 v66, 16, v60
	v_lshlrev_b32_e32 v182, 16, v61
	v_mul_f32_e32 v67, 0xbfb8aa3b, v66
	v_mul_f32_e32 v183, 0xbfb8aa3b, v182
	v_exp_f32_e32 v67, v67
	v_exp_f32_e32 v183, v183
	v_mov_b32_e32 v185, v36
	v_mov_b32_e32 v187, v38
	v_add_f32_e32 v36, 1.0, v67
	v_add_f32_e32 v38, 1.0, v183
	v_rcp_f32_e32 v184, v36
	v_rcp_f32_e32 v186, v38
	v_mov_b32_e32 v67, v62
	v_and_b32_e32 v62, 0xffff0000, v60
	v_mov_b32_e32 v183, v64
	v_and_b32_e32 v64, 0xffff0000, v61
	v_mul_f32_e32 v36, 0xbfb8aa3b, v62
	v_mul_f32_e32 v38, 0xbfb8aa3b, v64
	v_exp_f32_e32 v36, v36
	v_exp_f32_e32 v38, v38
	v_pk_mul_f32 v[60:61], v[184:185], v[66:67]
	v_pk_mul_f32 v[66:67], v[186:187], v[182:183]
	v_add_f32_e32 v36, 1.0, v36
	v_add_f32_e32 v38, 1.0, v38
	v_rcp_f32_e32 v36, v36
	v_rcp_f32_e32 v38, v38
	v_mul_f32_e32 v60, v60, v61
	v_mul_f32_e32 v61, v66, v67
	v_pk_mul_f32 v[36:37], v[36:37], v[62:63]
	v_pk_mul_f32 v[38:39], v[38:39], v[64:65]
; __device__ __forceinline__ unsigned cvt_pk(float lo, float hi) { unsigned r; asm volatile("v_cvt_pk_bf16_f32 %0, %1, %2" : "=v"(r) : "v"(lo), "v"(hi)); return r; }
; __device__ __forceinline__ float bflo(unsigned w) { return __uint_as_float(w << 16); }
; __device__ __forceinline__ float bfhi(unsigned w) { return __uint_as_float(w & 0xffff0000u); }
; __device__ __forceinline__ float silu(float x) { return x * sigm(x); }
; __device__ void phase_mix(const Params& p, unsigned char* smem) {
;     ...
; #pragma unroll
;             for (int nb = 0; nb < 8; ++nb) { const int d = nb * 16 + kq * 4;
;                 const u32x2 za = zreg[nb]; const f32x4 ps = *(const f32x4*)(p.pool_scale + g * 128 + d);
;                 u32x2 o; o.x = cvt_pk(acc[nb][0] * ps[0] * silu(bflo(za.x)), acc[nb][1] * ps[1] * silu(bfhi(za.x)));
;                 o.y = cvt_pk(acc[nb][2] * ps[2] * silu(bflo(za.y)), acc[nb][3] * ps[3] * silu(bfhi(za.y)));
;                 *(u32x2*)(CAT0 + r * 1024 + g * 128 + d) = o; }
	v_mul_f32_e32 v36, v36, v37
	v_mul_f32_e32 v37, v38, v39
	v_cvt_pk_bf16_f32 v36, v60, v36
	v_cvt_pk_bf16_f32 v37, v61, v37
	global_store_dwordx2 v[68:69], v[36:37], off offset:96
	v_mov_b64_e32 v[36:37], v[232:233]
	v_mov_b64_e32 v[38:39], v[234:235]
	v_lshlrev_b32_e32 v60, 16, v58
	v_lshlrev_b32_e32 v62, 16, v59
	v_mul_f32_e32 v61, 0xbfb8aa3b, v60
	v_mul_f32_e32 v63, 0xbfb8aa3b, v62
	v_exp_f32_e32 v61, v61
	v_exp_f32_e32 v63, v63
	v_mov_b32_e32 v65, v32
	v_mov_b32_e32 v67, v34
	v_add_f32_e32 v32, 1.0, v61
	v_add_f32_e32 v34, 1.0, v63
	v_rcp_f32_e32 v64, v32
	v_rcp_f32_e32 v66, v34
	v_mov_b32_e32 v61, v36
	v_and_b32_e32 v36, 0xffff0000, v58
	v_mov_b32_e32 v63, v38
	v_and_b32_e32 v38, 0xffff0000, v59
	v_mul_f32_e32 v32, 0xbfb8aa3b, v36
	v_mul_f32_e32 v34, 0xbfb8aa3b, v38
	v_exp_f32_e32 v32, v32
	v_exp_f32_e32 v34, v34
	v_pk_mul_f32 v[58:59], v[64:65], v[60:61]
	v_pk_mul_f32 v[60:61], v[66:67], v[62:63]
	v_add_f32_e32 v32, 1.0, v32
	v_add_f32_e32 v34, 1.0, v34
	v_rcp_f32_e32 v32, v32
	v_rcp_f32_e32 v34, v34
	v_mul_f32_e32 v58, v58, v59
	v_mul_f32_e32 v59, v60, v61
	v_pk_mul_f32 v[32:33], v[32:33], v[36:37]
	v_pk_mul_f32 v[34:35], v[34:35], v[38:39]
	v_mul_f32_e32 v32, v32, v33
	v_mul_f32_e32 v33, v34, v35
	v_cvt_pk_bf16_f32 v32, v58, v32
	v_cvt_pk_bf16_f32 v33, v59, v33
	global_store_dwordx2 v[68:69], v[32:33], off offset:128
	v_mov_b64_e32 v[32:33], v[236:237]
	v_mov_b64_e32 v[34:35], v[238:239]
	v_lshlrev_b32_e32 v36, 16, v56
	v_lshlrev_b32_e32 v38, 16, v57
	v_mul_f32_e32 v37, 0xbfb8aa3b, v36
	v_mul_f32_e32 v39, 0xbfb8aa3b, v38
	v_exp_f32_e32 v37, v37
	v_exp_f32_e32 v39, v39
	v_mov_b32_e32 v59, v28
	v_mov_b32_e32 v61, v30
	v_add_f32_e32 v28, 1.0, v37
	v_add_f32_e32 v30, 1.0, v39
	v_rcp_f32_e32 v58, v28
	v_rcp_f32_e32 v60, v30
	v_mov_b32_e32 v37, v32
	v_and_b32_e32 v32, 0xffff0000, v56
	v_mov_b32_e32 v39, v34
	v_and_b32_e32 v34, 0xffff0000, v57
	v_mul_f32_e32 v28, 0xbfb8aa3b, v32
	v_mul_f32_e32 v30, 0xbfb8aa3b, v34
	v_exp_f32_e32 v28, v28
	v_exp_f32_e32 v30, v30
	v_pk_mul_f32 v[36:37], v[58:59], v[36:37]
	v_pk_mul_f32 v[38:39], v[60:61], v[38:39]
	v_add_f32_e32 v28, 1.0, v28
	v_add_f32_e32 v30, 1.0, v30
	v_rcp_f32_e32 v28, v28
	v_rcp_f32_e32 v30, v30
	v_mul_f32_e32 v36, v36, v37
	v_mul_f32_e32 v37, v38, v39
	v_pk_mul_f32 v[28:29], v[28:29], v[32:33]
	v_pk_mul_f32 v[30:31], v[30:31], v[34:35]
	v_mul_f32_e32 v28, v28, v29
	v_mul_f32_e32 v29, v30, v31
	v_cvt_pk_bf16_f32 v28, v36, v28
	v_cvt_pk_bf16_f32 v29, v37, v29
	global_store_dwordx2 v[68:69], v[28:29], off offset:160
	v_mov_b64_e32 v[28:29], v[240:241]
	v_mov_b64_e32 v[30:31], v[242:243]
	v_lshlrev_b32_e32 v32, 16, v54
	v_lshlrev_b32_e32 v34, 16, v55
	v_mul_f32_e32 v33, 0xbfb8aa3b, v32
	v_mul_f32_e32 v35, 0xbfb8aa3b, v34
	v_exp_f32_e32 v33, v33
	v_exp_f32_e32 v35, v35
	v_mov_b32_e32 v37, v24
	v_mov_b32_e32 v39, v26
	v_add_f32_e32 v24, 1.0, v33
	v_add_f32_e32 v26, 1.0, v35
	v_rcp_f32_e32 v36, v24
	v_rcp_f32_e32 v38, v26
	v_mov_b32_e32 v33, v28
	v_and_b32_e32 v28, 0xffff0000, v54
	v_mov_b32_e32 v35, v30
	v_and_b32_e32 v30, 0xffff0000, v55
	v_mul_f32_e32 v24, 0xbfb8aa3b, v28
	v_mul_f32_e32 v26, 0xbfb8aa3b, v30
	v_exp_f32_e32 v24, v24
	v_exp_f32_e32 v26, v26
	v_pk_mul_f32 v[32:33], v[36:37], v[32:33]
	v_pk_mul_f32 v[34:35], v[38:39], v[34:35]
	v_add_f32_e32 v24, 1.0, v24
	v_add_f32_e32 v26, 1.0, v26
	v_rcp_f32_e32 v24, v24
	v_rcp_f32_e32 v26, v26
	v_mul_f32_e32 v32, v32, v33
	v_mul_f32_e32 v33, v34, v35
	v_pk_mul_f32 v[24:25], v[24:25], v[28:29]
	v_pk_mul_f32 v[26:27], v[26:27], v[30:31]
	v_mul_f32_e32 v24, v24, v25
	v_mul_f32_e32 v25, v26, v27
	v_cvt_pk_bf16_f32 v24, v32, v24
	v_cvt_pk_bf16_f32 v25, v33, v25
	global_store_dwordx2 v[68:69], v[24:25], off offset:192
	v_mov_b64_e32 v[24:25], v[244:245]
	v_mov_b64_e32 v[26:27], v[246:247]
	v_lshlrev_b32_e32 v28, 16, v52
	v_lshlrev_b32_e32 v32, 16, v53
	v_mov_b32_e32 v31, v20
	v_mov_b32_e32 v35, v22
	v_mul_f32_e32 v20, 0xbfb8aa3b, v28
	v_mul_f32_e32 v22, 0xbfb8aa3b, v32
	v_exp_f32_e32 v20, v20
	v_exp_f32_e32 v22, v22
	v_add_f32_e32 v20, 1.0, v20
	v_add_f32_e32 v22, 1.0, v22
	v_rcp_f32_e32 v30, v20
	v_rcp_f32_e32 v34, v22
	v_mov_b32_e32 v29, v24
	v_and_b32_e32 v24, 0xffff0000, v52
	v_mov_b32_e32 v33, v26
	v_and_b32_e32 v26, 0xffff0000, v53
	v_mul_f32_e32 v20, 0xbfb8aa3b, v24
	v_mul_f32_e32 v22, 0xbfb8aa3b, v26
	v_exp_f32_e32 v20, v20
	v_exp_f32_e32 v22, v22
	v_pk_mul_f32 v[28:29], v[30:31], v[28:29]
	v_pk_mul_f32 v[30:31], v[34:35], v[32:33]
	v_add_f32_e32 v20, 1.0, v20
	v_add_f32_e32 v22, 1.0, v22
	v_rcp_f32_e32 v20, v20
	v_rcp_f32_e32 v22, v22
	v_mul_f32_e32 v28, v28, v29
	v_mul_f32_e32 v29, v30, v31
	v_pk_mul_f32 v[20:21], v[20:21], v[24:25]
	v_pk_mul_f32 v[22:23], v[22:23], v[26:27]
	v_mul_f32_e32 v20, v20, v21
	v_mul_f32_e32 v21, v22, v23
	v_cvt_pk_bf16_f32 v20, v28, v20
	v_cvt_pk_bf16_f32 v21, v29, v21
	global_store_dwordx2 v[68:69], v[20:21], off offset:224
	s_cbranch_vccnz .LBB0_169

; __device__ __forceinline__ unsigned cvt_pk(float lo, float hi) { unsigned r; asm volatile("v_cvt_pk_bf16_f32 %0, %1, %2" : "=v"(r) : "v"(lo), "v"(hi)); return r; }
; __device__ __forceinline__ float bflo(unsigned w) { return __uint_as_float(w << 16); }
; __device__ __forceinline__ float bfhi(unsigned w) { return __uint_as_float(w & 0xffff0000u); }
; __device__ void phase_mix(const Params& p, unsigned char* smem) {
;     ...
;             { const int c2 = tid & 63, tq = tid >> 6;
;               float s0 = 0.f, s1 = 0.f; const int tl0 = tq * 16;
;               for (int j = tl0 - left; j <= tl0 + right; ++j) { const unsigned w = *(const unsigned*)(halo + (j + 8) * 256 + c2 * 4); s0 += bflo(w); s1 += bfhi(w); }
;               for (int tl = tl0; tl < tl0 + 16; ++tl) { const int t = ts0 + tl; const int lo = max(t - left, 0), hi = min(t + right + 1, T);
;                   const float inv = __builtin_amdgcn_rcpf((float)(hi - lo)); const unsigned xw = *(const unsigned*)(halo + (tl + 8) * 256 + c2 * 4);
;                   *(unsigned*)(As + swz(tl, c2 >> 2) + (c2 & 3) * 4) = cvt_pk(s0 * inv - bflo(xw), s1 * inv - bfhi(xw));
;                   const unsigned wn = *(const unsigned*)(halo + (tl + 1 + right + 8) * 256 + c2 * 4), wo = *(const unsigned*)(halo + (tl - left + 8) * 256 + c2 * 4);
;                   s0 += bflo(wn) - bflo(wo); s1 += bfhi(wn) - bfhi(wo); } }
.LBB0_155:
	s_or_b64 exec, exec, s[20:21]
	s_cmpk_lt_u32 s34, 0x100
	s_cselect_b32 s21, s33, 0x780
	s_cselect_b32 s20, s31, 0x800
	s_and_b32 s0, s21, s0
	v_add_u32_e32 v2, s0, v97
	v_subrev_u32_e32 v3, s29, v2
	v_or_b32_e32 v2, s29, v2
	v_max_i32_e32 v3, 0, v3
	v_min_i32_e32 v2, s20, v2
	v_sub_u32_e32 v2, v2, v3
	v_cvt_f32_i32_e32 v2, v2
	ds_read_b32 v3, v114 offset:2048
	v_mov_b32_e32 v8, 0
	v_rcp_iflag_f32_e32 v2, v2
	s_waitcnt lgkmcnt(0)
	v_lshlrev_b32_e32 v4, 16, v3
	v_and_b32_e32 v3, 0xffff0000, v3
	v_fma_f32 v4, v2, v1, -v4
	v_fma_f32 v2, v2, v0, -v3
	v_cvt_pk_bf16_f32 v2, v4, v2
	ds_write_b32 v115, v2
	ds_read_b32 v2, v116 offset:2048
	ds_read_b32 v3, v117 offset:2048
	ds_read_b32 v4, v118 offset:2048
	s_waitcnt lgkmcnt(2)
	v_lshlrev_b32_e32 v5, 16, v2
	s_waitcnt lgkmcnt(1)
	v_lshlrev_b32_e32 v6, 16, v3
	v_sub_f32_e32 v5, v5, v6
	v_add_u32_e32 v6, s0, v83
	v_subrev_u32_e32 v7, s29, v6
	v_add_u32_e32 v6, s29, v6
	v_max_i32_e32 v7, 0, v7
	v_min_i32_e32 v6, s20, v6
	v_sub_u32_e32 v6, v6, v7
	v_cvt_f32_i32_e32 v6, v6
	v_add_f32_e32 v1, v1, v5
	v_and_b32_e32 v2, 0xffff0000, v2
	v_and_b32_e32 v3, 0xffff0000, v3
	v_rcp_iflag_f32_e32 v5, v6
	v_sub_f32_e32 v2, v2, v3
	v_add_f32_e32 v0, v0, v2
	s_waitcnt lgkmcnt(0)
	v_lshlrev_b32_e32 v2, 16, v4
	v_fma_f32 v2, v5, v1, -v2
	v_and_b32_e32 v3, 0xffff0000, v4
	v_fma_f32 v3, v5, v0, -v3
	v_cvt_pk_bf16_f32 v2, v2, v3
	ds_write_b32 v119, v2
	ds_read_b32 v2, v120 offset:2048
	ds_read_b32 v3, v121 offset:2048
	ds_read_b32 v4, v122 offset:2048
	s_waitcnt lgkmcnt(2)
	v_lshlrev_b32_e32 v5, 16, v2
	s_waitcnt lgkmcnt(1)
	v_lshlrev_b32_e32 v6, 16, v3
	v_sub_f32_e32 v5, v5, v6
	v_add_u32_e32 v6, s0, v85
	v_subrev_u32_e32 v7, s29, v6
	v_add_u32_e32 v6, s29, v6
	v_max_i32_e32 v7, 0, v7
	v_min_i32_e32 v6, s20, v6
	v_sub_u32_e32 v6, v6, v7
	v_cvt_f32_i32_e32 v6, v6
	v_add_f32_e32 v1, v1, v5
	v_and_b32_e32 v2, 0xffff0000, v2
	v_and_b32_e32 v3, 0xffff0000, v3
	v_rcp_iflag_f32_e32 v5, v6
	v_sub_f32_e32 v2, v2, v3
	v_add_f32_e32 v0, v0, v2
	s_waitcnt lgkmcnt(0)
	v_lshlrev_b32_e32 v2, 16, v4
	v_fma_f32 v2, v5, v1, -v2
	v_and_b32_e32 v3, 0xffff0000, v4
	v_fma_f32 v3, v5, v0, -v3
	v_cvt_pk_bf16_f32 v2, v2, v3
	ds_write_b32 v123, v2
	ds_read_b32 v2, v124 offset:2048
	ds_read_b32 v3, v125 offset:2048
	ds_read_b32 v4, v126 offset:2048
	s_waitcnt lgkmcnt(2)
	v_lshlrev_b32_e32 v5, 16, v2
	s_waitcnt lgkmcnt(1)
	v_lshlrev_b32_e32 v6, 16, v3
	v_sub_f32_e32 v5, v5, v6
	v_add_u32_e32 v6, s0, v86
	v_subrev_u32_e32 v7, s29, v6
	v_add_u32_e32 v6, s29, v6
	v_max_i32_e32 v7, 0, v7
	v_min_i32_e32 v6, s20, v6
	v_sub_u32_e32 v6, v6, v7
	v_cvt_f32_i32_e32 v6, v6
	v_add_f32_e32 v1, v1, v5
	v_and_b32_e32 v2, 0xffff0000, v2
	v_and_b32_e32 v3, 0xffff0000, v3
	v_rcp_iflag_f32_e32 v5, v6
	v_sub_f32_e32 v2, v2, v3
	v_add_f32_e32 v0, v0, v2
	s_waitcnt lgkmcnt(0)
	v_lshlrev_b32_e32 v2, 16, v4
	v_fma_f32 v2, v5, v1, -v2
	v_and_b32_e32 v3, 0xffff0000, v4
	v_fma_f32 v3, v5, v0, -v3
	v_cvt_pk_bf16_f32 v2, v2, v3
	ds_write_b32 v127, v2
	ds_read_b32 v2, v128 offset:2048
	ds_read_b32 v3, v129 offset:2048
	ds_read_b32 v4, v130 offset:2048
	s_waitcnt lgkmcnt(2)
	v_lshlrev_b32_e32 v5, 16, v2
	s_waitcnt lgkmcnt(1)
	v_lshlrev_b32_e32 v6, 16, v3
	v_sub_f32_e32 v5, v5, v6
	v_add_u32_e32 v6, s0, v87
	v_subrev_u32_e32 v7, s29, v6
	v_add_u32_e32 v6, s29, v6
	v_max_i32_e32 v7, 0, v7
	v_min_i32_e32 v6, s20, v6
	v_sub_u32_e32 v6, v6, v7
	v_cvt_f32_i32_e32 v6, v6
	v_add_f32_e32 v1, v1, v5
	v_and_b32_e32 v2, 0xffff0000, v2
	v_and_b32_e32 v3, 0xffff0000, v3
	v_rcp_iflag_f32_e32 v5, v6
	v_sub_f32_e32 v2, v2, v3
	v_add_f32_e32 v0, v0, v2
	s_waitcnt lgkmcnt(0)
	v_lshlrev_b32_e32 v2, 16, v4
	v_fma_f32 v2, v5, v1, -v2
	v_and_b32_e32 v3, 0xffff0000, v4
	v_fma_f32 v3, v5, v0, -v3
	v_cvt_pk_bf16_f32 v2, v2, v3
	ds_write_b32 v131, v2
	ds_read_b32 v2, v132 offset:2048
	ds_read_b32 v3, v133 offset:2048
	ds_read_b32 v4, v134 offset:2048
	s_waitcnt lgkmcnt(2)
	v_lshlrev_b32_e32 v5, 16, v2
	s_waitcnt lgkmcnt(1)
	v_lshlrev_b32_e32 v6, 16, v3
	v_sub_f32_e32 v5, v5, v6
	v_add_u32_e32 v6, s0, v88
	v_subrev_u32_e32 v7, s29, v6
	v_add_u32_e32 v6, s29, v6
	v_max_i32_e32 v7, 0, v7
	v_min_i32_e32 v6, s20, v6
	v_sub_u32_e32 v6, v6, v7
	v_cvt_f32_i32_e32 v6, v6
	v_add_f32_e32 v1, v1, v5
	v_and_b32_e32 v2, 0xffff0000, v2
	v_and_b32_e32 v3, 0xffff0000, v3
	v_rcp_iflag_f32_e32 v5, v6
	v_sub_f32_e32 v2, v2, v3
	v_add_f32_e32 v0, v0, v2
	s_waitcnt lgkmcnt(0)
	v_lshlrev_b32_e32 v2, 16, v4
	v_fma_f32 v2, v5, v1, -v2
	v_and_b32_e32 v3, 0xffff0000, v4
	v_fma_f32 v3, v5, v0, -v3
	v_cvt_pk_bf16_f32 v2, v2, v3
	ds_write_b32 v135, v2
	ds_read_b32 v2, v136 offset:2048
	ds_read_b32 v3, v137 offset:2048
	ds_read_b32 v4, v138 offset:2048
	s_waitcnt lgkmcnt(2)
	v_lshlrev_b32_e32 v5, 16, v2
	s_waitcnt lgkmcnt(1)
	v_lshlrev_b32_e32 v6, 16, v3
	v_sub_f32_e32 v5, v5, v6
	v_add_u32_e32 v6, s0, v89
	v_subrev_u32_e32 v7, s29, v6
	v_add_u32_e32 v6, s29, v6
	v_max_i32_e32 v7, 0, v7
	v_min_i32_e32 v6, s20, v6
	v_sub_u32_e32 v6, v6, v7
	v_cvt_f32_i32_e32 v6, v6
	v_add_f32_e32 v1, v1, v5
	v_and_b32_e32 v2, 0xffff0000, v2
	v_and_b32_e32 v3, 0xffff0000, v3
	v_rcp_iflag_f32_e32 v5, v6
	v_sub_f32_e32 v2, v2, v3
	v_add_f32_e32 v0, v0, v2
	s_waitcnt lgkmcnt(0)
	v_lshlrev_b32_e32 v2, 16, v4
	v_fma_f32 v2, v5, v1, -v2
	v_and_b32_e32 v3, 0xffff0000, v4
	v_fma_f32 v3, v5, v0, -v3
	v_cvt_pk_bf16_f32 v2, v2, v3
	ds_write_b32 v139, v2
	ds_read_b32 v2, v140 offset:2048
	ds_read_b32 v3, v141 offset:2048
	ds_read_b32 v4, v142 offset:2048
	s_waitcnt lgkmcnt(2)
	v_lshlrev_b32_e32 v5, 16, v2
	s_waitcnt lgkmcnt(1)
; __device__ __forceinline__ unsigned cvt_pk(float lo, float hi) { unsigned r; asm volatile("v_cvt_pk_bf16_f32 %0, %1, %2" : "=v"(r) : "v"(lo), "v"(hi)); return r; }
; __device__ __forceinline__ float bflo(unsigned w) { return __uint_as_float(w << 16); }
; __device__ __forceinline__ float bfhi(unsigned w) { return __uint_as_float(w & 0xffff0000u); }
; __device__ void phase_mix(const Params& p, unsigned char* smem) {
;     ...
;               for (int tl = tl0; tl < tl0 + 16; ++tl) { const int t = ts0 + tl; const int lo = max(t - left, 0), hi = min(t + right + 1, T);
;                   const float inv = __builtin_amdgcn_rcpf((float)(hi - lo)); const unsigned xw = *(const unsigned*)(halo + (tl + 8) * 256 + c2 * 4);
;                   *(unsigned*)(As + swz(tl, c2 >> 2) + (c2 & 3) * 4) = cvt_pk(s0 * inv - bflo(xw), s1 * inv - bfhi(xw));
;                   const unsigned wn = *(const unsigned*)(halo + (tl + 1 + right + 8) * 256 + c2 * 4), wo = *(const unsigned*)(halo + (tl - left + 8) * 256 + c2 * 4);
;                   s0 += bflo(wn) - bflo(wo); s1 += bfhi(wn) - bfhi(wo); } }
	v_lshlrev_b32_e32 v6, 16, v3
	v_sub_f32_e32 v5, v5, v6
	v_add_u32_e32 v6, s0, v90
	v_subrev_u32_e32 v7, s29, v6
	v_add_u32_e32 v6, s29, v6
	v_max_i32_e32 v7, 0, v7
	v_min_i32_e32 v6, s20, v6
	v_sub_u32_e32 v6, v6, v7
	v_cvt_f32_i32_e32 v6, v6
	v_add_f32_e32 v1, v1, v5
	v_and_b32_e32 v2, 0xffff0000, v2
	v_and_b32_e32 v3, 0xffff0000, v3
	v_rcp_iflag_f32_e32 v5, v6
	v_sub_f32_e32 v2, v2, v3
	v_add_f32_e32 v0, v0, v2
	s_waitcnt lgkmcnt(0)
	v_lshlrev_b32_e32 v2, 16, v4
	v_fma_f32 v2, v5, v1, -v2
	v_and_b32_e32 v3, 0xffff0000, v4
	v_fma_f32 v3, v5, v0, -v3
	v_cvt_pk_bf16_f32 v2, v2, v3
	ds_write_b32 v143, v2
	ds_read_b32 v2, v144 offset:2048
	ds_read_b32 v3, v145 offset:2048
	ds_read_b32 v4, v146 offset:2048
	s_waitcnt lgkmcnt(2)
	v_lshlrev_b32_e32 v5, 16, v2
	s_waitcnt lgkmcnt(1)
	v_lshlrev_b32_e32 v6, 16, v3
	v_sub_f32_e32 v5, v5, v6
	v_add_u32_e32 v6, s0, v91
	v_subrev_u32_e32 v7, s29, v6
	v_add_u32_e32 v6, s29, v6
	v_max_i32_e32 v7, 0, v7
	v_min_i32_e32 v6, s20, v6
	v_sub_u32_e32 v6, v6, v7
	v_cvt_f32_i32_e32 v6, v6
	v_add_f32_e32 v1, v1, v5
	v_and_b32_e32 v2, 0xffff0000, v2
	v_and_b32_e32 v3, 0xffff0000, v3
	v_rcp_iflag_f32_e32 v5, v6
	v_sub_f32_e32 v2, v2, v3
	v_add_f32_e32 v0, v0, v2
	s_waitcnt lgkmcnt(0)
	v_lshlrev_b32_e32 v2, 16, v4
	v_fma_f32 v2, v5, v1, -v2
	v_and_b32_e32 v3, 0xffff0000, v4
	v_fma_f32 v3, v5, v0, -v3
	v_cvt_pk_bf16_f32 v2, v2, v3
	ds_write_b32 v147, v2
	ds_read_b32 v2, v148 offset:2048
	ds_read_b32 v3, v149 offset:2048
	ds_read_b32 v4, v150 offset:2048
	s_waitcnt lgkmcnt(2)
	v_lshlrev_b32_e32 v5, 16, v2
	s_waitcnt lgkmcnt(1)
	v_lshlrev_b32_e32 v6, 16, v3
	v_sub_f32_e32 v5, v5, v6
	v_add_u32_e32 v6, s0, v92
	v_subrev_u32_e32 v7, s29, v6
	v_add_u32_e32 v6, s29, v6
	v_max_i32_e32 v7, 0, v7
	v_min_i32_e32 v6, s20, v6
	v_sub_u32_e32 v6, v6, v7
	v_cvt_f32_i32_e32 v6, v6
	v_add_f32_e32 v1, v1, v5
	v_and_b32_e32 v2, 0xffff0000, v2
	v_and_b32_e32 v3, 0xffff0000, v3
	v_rcp_iflag_f32_e32 v5, v6
	v_sub_f32_e32 v2, v2, v3
	v_add_f32_e32 v0, v0, v2
	s_waitcnt lgkmcnt(0)
	v_lshlrev_b32_e32 v2, 16, v4
	v_fma_f32 v2, v5, v1, -v2
	v_and_b32_e32 v3, 0xffff0000, v4
	v_fma_f32 v3, v5, v0, -v3
	v_cvt_pk_bf16_f32 v2, v2, v3
	ds_write_b32 v151, v2
	ds_read_b32 v2, v152 offset:2048
	ds_read_b32 v3, v153 offset:2048
	ds_read_b32 v4, v154 offset:2048
	s_waitcnt lgkmcnt(2)
	v_lshlrev_b32_e32 v5, 16, v2
	s_waitcnt lgkmcnt(1)
	v_lshlrev_b32_e32 v6, 16, v3
	v_sub_f32_e32 v5, v5, v6
	v_add_u32_e32 v6, s0, v93
	v_subrev_u32_e32 v7, s29, v6
	v_add_u32_e32 v6, s29, v6
	v_max_i32_e32 v7, 0, v7
	v_min_i32_e32 v6, s20, v6
	v_sub_u32_e32 v6, v6, v7
	v_cvt_f32_i32_e32 v6, v6
	v_add_f32_e32 v1, v1, v5
	v_and_b32_e32 v2, 0xffff0000, v2
	v_and_b32_e32 v3, 0xffff0000, v3
	v_rcp_iflag_f32_e32 v5, v6
	v_sub_f32_e32 v2, v2, v3
	v_add_f32_e32 v0, v0, v2
	s_waitcnt lgkmcnt(0)
	v_lshlrev_b32_e32 v2, 16, v4
	v_fma_f32 v2, v5, v1, -v2
	v_and_b32_e32 v3, 0xffff0000, v4
	v_fma_f32 v3, v5, v0, -v3
	v_cvt_pk_bf16_f32 v2, v2, v3
	ds_write_b32 v155, v2
	ds_read_b32 v2, v156 offset:2048
	ds_read_b32 v3, v157 offset:2048
	ds_read_b32 v4, v158 offset:2048
	s_waitcnt lgkmcnt(2)
	v_lshlrev_b32_e32 v5, 16, v2
	s_waitcnt lgkmcnt(1)
	v_lshlrev_b32_e32 v6, 16, v3
	v_sub_f32_e32 v5, v5, v6
	v_add_u32_e32 v6, s0, v102
	v_subrev_u32_e32 v7, s29, v6
	v_add_u32_e32 v6, s29, v6
	v_max_i32_e32 v7, 0, v7
	v_min_i32_e32 v6, s20, v6
	v_sub_u32_e32 v6, v6, v7
	v_cvt_f32_i32_e32 v6, v6
	v_add_f32_e32 v1, v1, v5
	v_and_b32_e32 v2, 0xffff0000, v2
	v_and_b32_e32 v3, 0xffff0000, v3
	v_rcp_iflag_f32_e32 v5, v6
	v_sub_f32_e32 v2, v2, v3
	v_add_f32_e32 v0, v0, v2
	s_waitcnt lgkmcnt(0)
	v_lshlrev_b32_e32 v2, 16, v4
	v_fma_f32 v2, v5, v1, -v2
	v_and_b32_e32 v3, 0xffff0000, v4
	v_fma_f32 v3, v5, v0, -v3
	v_cvt_pk_bf16_f32 v2, v2, v3
	ds_write_b32 v159, v2
	ds_read_b32 v2, v160 offset:2048
	ds_read_b32 v3, v161 offset:2048
	ds_read_b32 v4, v162 offset:2048
	s_waitcnt lgkmcnt(2)
; __device__ __forceinline__ unsigned cvt_pk(float lo, float hi) { unsigned r; asm volatile("v_cvt_pk_bf16_f32 %0, %1, %2" : "=v"(r) : "v"(lo), "v"(hi)); return r; }
; __device__ __forceinline__ float bflo(unsigned w) { return __uint_as_float(w << 16); }
; __device__ __forceinline__ float bfhi(unsigned w) { return __uint_as_float(w & 0xffff0000u); }
; __device__ void phase_mix(const Params& p, unsigned char* smem) {
;     ...
;               for (int tl = tl0; tl < tl0 + 16; ++tl) { const int t = ts0 + tl; const int lo = max(t - left, 0), hi = min(t + right + 1, T);
;                   const float inv = __builtin_amdgcn_rcpf((float)(hi - lo)); const unsigned xw = *(const unsigned*)(halo + (tl + 8) * 256 + c2 * 4);
;                   *(unsigned*)(As + swz(tl, c2 >> 2) + (c2 & 3) * 4) = cvt_pk(s0 * inv - bflo(xw), s1 * inv - bfhi(xw));
;                   const unsigned wn = *(const unsigned*)(halo + (tl + 1 + right + 8) * 256 + c2 * 4), wo = *(const unsigned*)(halo + (tl - left + 8) * 256 + c2 * 4);
;                   s0 += bflo(wn) - bflo(wo); s1 += bfhi(wn) - bfhi(wo); } }
;             __syncthreads();
;             HLOAD((tile_ + tstep < tlim) ? tile_ + tstep : tile_);
	v_lshlrev_b32_e32 v5, 16, v2
	s_waitcnt lgkmcnt(1)
	v_lshlrev_b32_e32 v6, 16, v3
	v_sub_f32_e32 v5, v5, v6
	v_add_u32_e32 v6, s0, v103
	v_subrev_u32_e32 v7, s29, v6
	v_add_u32_e32 v6, s29, v6
	v_max_i32_e32 v7, 0, v7
	v_min_i32_e32 v6, s20, v6
	v_sub_u32_e32 v6, v6, v7
	v_cvt_f32_i32_e32 v6, v6
	v_add_f32_e32 v1, v1, v5
	v_and_b32_e32 v2, 0xffff0000, v2
	v_and_b32_e32 v3, 0xffff0000, v3
	v_rcp_iflag_f32_e32 v5, v6
	v_sub_f32_e32 v2, v2, v3
	v_add_f32_e32 v0, v0, v2
	s_waitcnt lgkmcnt(0)
	v_lshlrev_b32_e32 v2, 16, v4
	v_fma_f32 v2, v5, v1, -v2
	v_and_b32_e32 v3, 0xffff0000, v4
	v_fma_f32 v3, v5, v0, -v3
	v_cvt_pk_bf16_f32 v2, v2, v3
	ds_write_b32 v163, v2
	ds_read_b32 v2, v164 offset:2048
	ds_read_b32 v3, v165 offset:2048
	ds_read_b32 v4, v166 offset:2048
	s_waitcnt lgkmcnt(2)
	v_lshlrev_b32_e32 v5, 16, v2
	s_waitcnt lgkmcnt(1)
	v_lshlrev_b32_e32 v6, 16, v3
	v_sub_f32_e32 v5, v5, v6
	v_add_u32_e32 v6, s0, v105
	v_subrev_u32_e32 v7, s29, v6
	v_add_u32_e32 v6, s29, v6
	v_max_i32_e32 v7, 0, v7
	v_min_i32_e32 v6, s20, v6
	v_sub_u32_e32 v6, v6, v7
	v_cvt_f32_i32_e32 v6, v6
	v_add_f32_e32 v1, v1, v5
	v_and_b32_e32 v2, 0xffff0000, v2
	v_and_b32_e32 v3, 0xffff0000, v3
	v_rcp_iflag_f32_e32 v5, v6
	v_sub_f32_e32 v2, v2, v3
	v_add_f32_e32 v0, v0, v2
	s_waitcnt lgkmcnt(0)
	v_lshlrev_b32_e32 v2, 16, v4
	v_fma_f32 v2, v5, v1, -v2
	v_and_b32_e32 v3, 0xffff0000, v4
	v_fma_f32 v3, v5, v0, -v3
	v_cvt_pk_bf16_f32 v2, v2, v3
	ds_write_b32 v167, v2
	ds_read_b32 v2, v168 offset:2048
	ds_read_b32 v3, v169 offset:2048
	ds_read_b32 v4, v171 offset:2048
	s_waitcnt lgkmcnt(2)
	v_lshlrev_b32_e32 v5, 16, v2
	s_waitcnt lgkmcnt(1)
	v_lshlrev_b32_e32 v6, 16, v3
	v_sub_f32_e32 v5, v5, v6
	v_add_u32_e32 v6, s0, v106
	v_subrev_u32_e32 v7, s29, v6
	v_add_u32_e32 v6, s29, v6
	v_max_i32_e32 v7, 0, v7
	v_min_i32_e32 v6, s20, v6
	v_sub_u32_e32 v6, v6, v7
	v_cvt_f32_i32_e32 v6, v6
	v_add_f32_e32 v1, v1, v5
	v_and_b32_e32 v2, 0xffff0000, v2
	v_and_b32_e32 v3, 0xffff0000, v3
	v_rcp_iflag_f32_e32 v5, v6
	v_sub_f32_e32 v2, v2, v3
	v_add_f32_e32 v0, v0, v2
	s_waitcnt lgkmcnt(0)
	v_lshlrev_b32_e32 v2, 16, v4
	v_fma_f32 v2, v5, v1, -v2
	v_and_b32_e32 v3, 0xffff0000, v4
	v_fma_f32 v3, v5, v0, -v3
	v_cvt_pk_bf16_f32 v2, v2, v3
	ds_write_b32 v172, v2
	ds_read_b32 v2, v173 offset:2048
	ds_read_b32 v3, v174 offset:2048
	ds_read_b32 v4, v175 offset:2048
	s_waitcnt lgkmcnt(2)
	v_lshlrev_b32_e32 v5, 16, v2
	s_waitcnt lgkmcnt(1)
	v_lshlrev_b32_e32 v6, 16, v3
	v_sub_f32_e32 v5, v5, v6
	v_add_u32_e32 v6, s0, v107
	v_subrev_u32_e32 v7, s29, v6
	v_add_u32_e32 v6, s29, v6
	v_max_i32_e32 v7, 0, v7
	v_min_i32_e32 v6, s20, v6
	s_add_i32 s0, s34, s3
	v_sub_u32_e32 v6, v6, v7
	s_cmpk_gt_u32 s0, 0x1ff
	v_cvt_f32_i32_e32 v6, v6
	s_cselect_b64 s[20:21], -1, 0
	s_cmpk_lt_u32 s0, 0x200
	s_cselect_b32 s22, s0, s34
	s_lshl_b32 s22, s22, 7
	s_and_b32 s23, s22, 0xff80
	v_add_f32_e32 v1, v1, v5
	v_rcp_iflag_f32_e32 v5, v6
	s_cmpk_lt_u32 s23, 0x8000
	v_and_b32_e32 v2, 0xffff0000, v2
	v_and_b32_e32 v3, 0xffff0000, v3
	s_cselect_b32 s34, s33, 0x780
	v_sub_f32_e32 v2, v2, v3
	s_cselect_b32 s35, s31, 0x800
	s_and_b32 s36, s34, s22
	v_add_f32_e32 v0, v0, v2
	s_waitcnt lgkmcnt(0)
	v_lshlrev_b32_e32 v2, 16, v4
	s_sub_i32 s34, s23, s36
	s_add_i32 s36, s36, -8
	v_fma_f32 v1, v5, v1, -v2
	v_and_b32_e32 v2, 0xffff0000, v4
	v_add_u32_e32 v4, s36, v84
	v_fma_f32 v0, v5, v0, -v2
	v_cmp_lt_i32_e32 vcc, -1, v4
	v_cvt_pk_bf16_f32 v0, v1, v0
	s_and_b64 s[22:23], s[4:5], vcc
	v_cmp_gt_i32_e32 vcc, s35, v4
	ds_write_b32 v177, v0
	s_and_b64 s[38:39], s[22:23], vcc
	v_mov_b32_e32 v0, 0
	v_mov_b32_e32 v1, 0
	v_mov_b32_e32 v2, 0
	v_mov_b32_e32 v3, 0
	s_waitcnt lgkmcnt(0)
	s_barrier
	s_waitcnt vmcnt(0)
	s_and_saveexec_b64 s[22:23], s[38:39]
	s_cbranch_execz .LBB0_157
	v_add_u32_e32 v0, s34, v4
	v_mad_i64_i32 v[0:1], s[38:39], v0, s30, v[42:43]
	global_load_dwordx4 v[0:3], v[0:1], off
